# speedup vs baseline: 1.0101x; 1.0101x over previous
;     __device__ __forceinline__ float* mod() const { return (float*)(ws + OFF_mod); }
; DEV void resid_big(const Params& p, int l, int mt, int nt, const bf16_t* A, int K, const bf16_t* W, int gate_off, bool res_from_input, char* smem) {
;     ...
;     for (int mi = 0; mi < 4; ++mi) {
;         const int row = rbase + mi * 16;
;         const float* gt = p.mod() + (size_t)(l * 9 + mod_index(row)) * 6144 + gate_off + c0;
;         const float* res = res_from_input ? xrow(p, l, row) : p.out + (size_t)row * 1024;
;         float* dst = p.out + (size_t)row * 1024;
; #pragma unroll
;         for (int ni = 0; ni < 8; ++ni) {
;             const f32x4 g4 = *(const f32x4*)(gt + ni * 16), r4 = *(const f32x4*)(res + c0 + ni * 16);
;             *(f32x4*)(dst + c0 + ni * 16) = r4 + g4 * acc[mi][ni];
;         }
;     }
.LBB0_62:
	v_lshrrev_b32_e32 v34, 4, v34
	v_add_u32_e32 v34, 1, v34
	v_lshlrev_b64 v[36:37], 12, v[36:37]
	v_cndmask_b32_e64 v34, v34, 0, s[0:1]
	v_lshl_add_u64 v[36:37], v[40:41], 0, v[36:37]
	v_add_u32_e32 v40, s20, v34
	v_mov_b64_e32 v[34:35], s[12:13]
	v_mad_i64_i32 v[34:35], s[0:1], v40, s33, v[34:35]
	v_lshl_add_u64 v[34:35], v[34:35], 0, v[32:33]
	s_mov_b64 s[0:1], 0x2000
	s_movk_i32 s30, 0x2000
	v_lshlrev_b64 v[38:39], 12, v[38:39]
	v_lshl_add_u64 v[42:43], v[34:35], 0, s[0:1]
	v_add_co_u32_e32 v34, vcc, s30, v34
	v_lshl_add_u64 v[38:39], s[92:93], 0, v[38:39]
	s_nop 0
	v_addc_co_u32_e32 v35, vcc, 0, v35, vcc
	v_lshl_add_u64 v[44:45], v[36:37], 0, v[32:33]
	v_lshl_add_u64 v[46:47], v[38:39], 0, v[32:33]
	v_readlane_b32 s0, v254, 4
	s_add_i32 s28, s28, s0
	s_add_i32 s23, s23, s0
	s_add_i32 s21, s21, s22
	s_cmpk_gt_i32 s28, 0x1ff
	v_readlane_b32 s1, v254, 5
	flat_load_dwordx4 v[206:209], v[34:35]
	flat_load_dwordx4 v[210:213], v[42:43] offset:64
	flat_load_dwordx4 v[214:217], v[42:43] offset:128
	flat_load_dwordx4 v[218:221], v[42:43] offset:192
	flat_load_dwordx4 v[222:225], v[42:43] offset:256
	flat_load_dwordx4 v[226:229], v[42:43] offset:320
	flat_load_dwordx4 v[230:233], v[42:43] offset:384
	flat_load_dwordx4 v[234:237], v[42:43] offset:448
	flat_load_dwordx4 v[238:241], v[44:45]
	flat_load_dwordx4 v[242:245], v[44:45] offset:64
	flat_load_dwordx4 v[246:249], v[44:45] offset:128
	flat_load_dwordx4 v[158:161], v[44:45] offset:192
	flat_load_dwordx4 v[162:165], v[44:45] offset:256
	flat_load_dwordx4 v[166:169], v[44:45] offset:320
	flat_load_dwordx4 v[170:173], v[44:45] offset:384
	flat_load_dwordx4 v[174:177], v[44:45] offset:448
	s_waitcnt vmcnt(0) lgkmcnt(0)
	v_pk_fma_f32 v[238:239], v[28:29], v[206:207], v[238:239]
	v_pk_fma_f32 v[240:241], v[30:31], v[208:209], v[240:241]
	v_pk_fma_f32 v[242:243], v[24:25], v[210:211], v[242:243]
	v_pk_fma_f32 v[244:245], v[26:27], v[212:213], v[244:245]
	v_pk_fma_f32 v[246:247], v[20:21], v[214:215], v[246:247]
	v_pk_fma_f32 v[248:249], v[22:23], v[216:217], v[248:249]
	v_pk_fma_f32 v[158:159], v[16:17], v[218:219], v[158:159]
	v_pk_fma_f32 v[160:161], v[18:19], v[220:221], v[160:161]
	v_pk_fma_f32 v[162:163], v[12:13], v[222:223], v[162:163]
	v_pk_fma_f32 v[164:165], v[14:15], v[224:225], v[164:165]
	v_pk_fma_f32 v[166:167], v[8:9], v[226:227], v[166:167]
	v_pk_fma_f32 v[168:169], v[10:11], v[228:229], v[168:169]
	v_pk_fma_f32 v[170:171], v[4:5], v[230:231], v[170:171]
	v_pk_fma_f32 v[172:173], v[6:7], v[232:233], v[172:173]
	v_pk_fma_f32 v[174:175], v[0:1], v[234:235], v[174:175]
	v_pk_fma_f32 v[176:177], v[2:3], v[236:237], v[176:177]
	flat_store_dwordx4 v[46:47], v[238:241]
	flat_store_dwordx4 v[46:47], v[242:245] offset:64
	flat_store_dwordx4 v[46:47], v[246:249] offset:128
	flat_store_dwordx4 v[46:47], v[158:161] offset:192
	flat_store_dwordx4 v[46:47], v[162:165] offset:256
	flat_store_dwordx4 v[46:47], v[166:169] offset:320
	flat_store_dwordx4 v[46:47], v[170:173] offset:384
	flat_store_dwordx4 v[46:47], v[174:177] offset:448
	s_nop 1
	s_cbranch_scc1 .LBB0_96

;     __device__ __forceinline__ float* mod() const { return (float*)(ws + OFF_mod); }
; DEV void resid_big(const Params& p, int l, int mt, int nt, const bf16_t* A, int K, const bf16_t* W, int gate_off, bool res_from_input, char* smem) {
;     ...
;     for (int mi = 0; mi < 4; ++mi) {
;         const int row = rbase + mi * 16;
;         const float* gt = p.mod() + (size_t)(l * 9 + mod_index(row)) * 6144 + gate_off + c0;
;         const float* res = res_from_input ? xrow(p, l, row) : p.out + (size_t)row * 1024;
;         float* dst = p.out + (size_t)row * 1024;
; #pragma unroll
;         for (int ni = 0; ni < 8; ++ni) {
;             const f32x4 g4 = *(const f32x4*)(gt + ni * 16), r4 = *(const f32x4*)(res + c0 + ni * 16);
;             *(f32x4*)(dst + c0 + ni * 16) = r4 + g4 * acc[mi][ni];
;         }
;     }
.LBB0_73:
	v_lshrrev_b32_e32 v132, 4, v132
	v_lshlrev_b32_e32 v133, 1, v32
	v_lshrrev_b32_e32 v32, 2, v32
	v_or_b32_e32 v132, 1, v132
	v_and_b32_e32 v133, 0x80, v133
	v_and_b32_e32 v32, 12, v32
	v_cndmask_b32_e64 v132, v132, 0, s[0:1]
	v_or3_b32 v32, v133, v32, s14
	v_add_u32_e32 v138, s20, v132
	v_mov_b64_e32 v[132:133], s[12:13]
	v_mad_i64_i32 v[132:133], s[0:1], v138, s33, v[132:133]
	v_lshlrev_b32_e32 v32, 2, v32
	v_lshl_add_u64 v[140:141], v[132:133], 0, v[32:33]
	v_lshlrev_b64 v[132:133], 12, v[134:135]
	v_lshl_add_u64 v[132:133], v[136:137], 0, v[132:133]
	v_add_co_u32_e32 v136, vcc, s34, v140
	v_lshl_add_u64 v[142:143], v[132:133], 0, v[32:33]
	s_nop 0
	v_addc_co_u32_e32 v137, vcc, 0, v141, vcc
	v_lshlrev_b64 v[144:145], 12, v[130:131]
	v_lshl_add_u64 v[144:145], s[92:93], 0, v[144:145]
	v_lshl_add_u64 v[144:145], v[144:145], 0, v[32:33]
	s_mov_b64 s[0:1], 0x2000
	v_lshl_add_u64 v[140:141], v[140:141], 0, s[0:1]
	s_movk_i32 s0, 0x4000
	s_andn2_b64 vcc, exec, s[10:11]
	s_mov_b64 s[14:15], -1
	flat_load_dwordx4 v[206:209], v[136:137]
	flat_load_dwordx4 v[210:213], v[140:141] offset:64
	flat_load_dwordx4 v[214:217], v[140:141] offset:128
	flat_load_dwordx4 v[218:221], v[140:141] offset:192
	flat_load_dwordx4 v[222:225], v[140:141] offset:256
	flat_load_dwordx4 v[226:229], v[140:141] offset:320
	flat_load_dwordx4 v[230:233], v[140:141] offset:384
	flat_load_dwordx4 v[234:237], v[140:141] offset:448
	flat_load_dwordx4 v[238:241], v[142:143]
	flat_load_dwordx4 v[242:245], v[142:143] offset:64
	flat_load_dwordx4 v[246:249], v[142:143] offset:128
	flat_load_dwordx4 v[158:161], v[142:143] offset:192
	flat_load_dwordx4 v[162:165], v[142:143] offset:256
	flat_load_dwordx4 v[166:169], v[142:143] offset:320
	flat_load_dwordx4 v[170:173], v[142:143] offset:384
	flat_load_dwordx4 v[174:177], v[142:143] offset:448
	s_waitcnt vmcnt(0) lgkmcnt(0)
	v_pk_fma_f32 v[238:239], v[126:127], v[206:207], v[238:239]
	v_pk_fma_f32 v[240:241], v[128:129], v[208:209], v[240:241]
	v_pk_fma_f32 v[242:243], v[122:123], v[210:211], v[242:243]
	v_pk_fma_f32 v[244:245], v[124:125], v[212:213], v[244:245]
	v_pk_fma_f32 v[246:247], v[118:119], v[214:215], v[246:247]
	v_pk_fma_f32 v[248:249], v[120:121], v[216:217], v[248:249]
	v_pk_fma_f32 v[158:159], v[114:115], v[218:219], v[158:159]
	v_pk_fma_f32 v[160:161], v[116:117], v[220:221], v[160:161]
	v_pk_fma_f32 v[162:163], v[110:111], v[222:223], v[162:163]
	v_pk_fma_f32 v[164:165], v[112:113], v[224:225], v[164:165]
	v_pk_fma_f32 v[166:167], v[106:107], v[226:227], v[166:167]
	v_pk_fma_f32 v[168:169], v[108:109], v[228:229], v[168:169]
	v_pk_fma_f32 v[170:171], v[102:103], v[230:231], v[170:171]
	v_pk_fma_f32 v[172:173], v[104:105], v[232:233], v[172:173]
	v_pk_fma_f32 v[174:175], v[98:99], v[234:235], v[174:175]
	v_pk_fma_f32 v[176:177], v[100:101], v[236:237], v[176:177]
	flat_store_dwordx4 v[144:145], v[238:241]
	flat_store_dwordx4 v[144:145], v[242:245] offset:64
	flat_store_dwordx4 v[144:145], v[246:249] offset:128
	flat_store_dwordx4 v[144:145], v[158:161] offset:192
	flat_store_dwordx4 v[144:145], v[162:165] offset:256
	flat_store_dwordx4 v[144:145], v[166:169] offset:320
	flat_store_dwordx4 v[144:145], v[170:173] offset:384
	flat_store_dwordx4 v[144:145], v[174:177] offset:448
	s_nop 1
	v_or_b32_e32 v102, 16, v130
	v_cndmask_b32_e64 v103, 0, 1, s[10:11]
	v_cmp_gt_i32_e64 s[6:7], s0, v102
	s_movk_i32 s0, 0x3fff
	v_cmp_lt_i32_e64 s[4:5], s0, v102
	v_cmp_ne_u32_e64 s[0:1], 1, v103
	s_cbranch_vccnz .LBB0_75
	v_ashrrev_i32_e32 v103, 31, v102
	s_mov_b64 s[14:15], 0

;     __device__ __forceinline__ float* mod() const { return (float*)(ws + OFF_mod); }
; DEV void resid_big(const Params& p, int l, int mt, int nt, const bf16_t* A, int K, const bf16_t* W, int gate_off, bool res_from_input, char* smem) {
;     ...
;     for (int mi = 0; mi < 4; ++mi) {
;         const int row = rbase + mi * 16;
;         const float* gt = p.mod() + (size_t)(l * 9 + mod_index(row)) * 6144 + gate_off + c0;
;         const float* res = res_from_input ? xrow(p, l, row) : p.out + (size_t)row * 1024;
;         float* dst = p.out + (size_t)row * 1024;
; #pragma unroll
;         for (int ni = 0; ni < 8; ++ni) {
;             const f32x4 g4 = *(const f32x4*)(gt + ni * 16), r4 = *(const f32x4*)(res + c0 + ni * 16);
;             *(f32x4*)(dst + c0 + ni * 16) = r4 + g4 * acc[mi][ni];
;         }
;     }
.LBB0_81:
	v_lshrrev_b32_e32 v98, 4, v98
	v_add_u32_e32 v98, 1, v98
	v_cndmask_b32_e64 v98, v98, 0, s[6:7]
	v_add_u32_e32 v106, s20, v98
	v_mov_b64_e32 v[98:99], s[12:13]
	v_mad_i64_i32 v[98:99], s[4:5], v106, s33, v[98:99]
	v_lshl_add_u64 v[108:109], v[98:99], 0, v[32:33]
	v_lshlrev_b64 v[98:99], 12, v[100:101]
	v_lshl_add_u64 v[98:99], v[104:105], 0, v[98:99]
	v_add_co_u32_e32 v104, vcc, s34, v108
	v_lshl_add_u64 v[110:111], v[98:99], 0, v[32:33]
	s_nop 0
	v_addc_co_u32_e32 v105, vcc, 0, v109, vcc
	v_lshlrev_b64 v[102:103], 12, v[102:103]
	v_lshl_add_u64 v[102:103], s[92:93], 0, v[102:103]
	v_lshl_add_u64 v[102:103], v[102:103], 0, v[32:33]
	s_mov_b64 s[4:5], 0x2000
	v_lshl_add_u64 v[108:109], v[108:109], 0, s[4:5]
	s_movk_i32 s4, 0x4000
	s_and_b64 vcc, exec, s[0:1]
	s_mov_b64 s[14:15], -1
	flat_load_dwordx4 v[206:209], v[104:105]
	flat_load_dwordx4 v[210:213], v[108:109] offset:64
	flat_load_dwordx4 v[214:217], v[108:109] offset:128
	flat_load_dwordx4 v[218:221], v[108:109] offset:192
	flat_load_dwordx4 v[222:225], v[108:109] offset:256
	flat_load_dwordx4 v[226:229], v[108:109] offset:320
	flat_load_dwordx4 v[230:233], v[108:109] offset:384
	flat_load_dwordx4 v[234:237], v[108:109] offset:448
	flat_load_dwordx4 v[238:241], v[110:111]
	flat_load_dwordx4 v[242:245], v[110:111] offset:64
	flat_load_dwordx4 v[246:249], v[110:111] offset:128
	flat_load_dwordx4 v[158:161], v[110:111] offset:192
	flat_load_dwordx4 v[162:165], v[110:111] offset:256
	flat_load_dwordx4 v[166:169], v[110:111] offset:320
	flat_load_dwordx4 v[170:173], v[110:111] offset:384
	flat_load_dwordx4 v[174:177], v[110:111] offset:448
	s_waitcnt vmcnt(0) lgkmcnt(0)
	v_pk_fma_f32 v[238:239], v[94:95], v[206:207], v[238:239]
	v_pk_fma_f32 v[240:241], v[96:97], v[208:209], v[240:241]
	v_pk_fma_f32 v[242:243], v[90:91], v[210:211], v[242:243]
	v_pk_fma_f32 v[244:245], v[92:93], v[212:213], v[244:245]
	v_pk_fma_f32 v[246:247], v[86:87], v[214:215], v[246:247]
	v_pk_fma_f32 v[248:249], v[88:89], v[216:217], v[248:249]
	v_pk_fma_f32 v[158:159], v[82:83], v[218:219], v[158:159]
	v_pk_fma_f32 v[160:161], v[84:85], v[220:221], v[160:161]
	v_pk_fma_f32 v[162:163], v[78:79], v[222:223], v[162:163]
	v_pk_fma_f32 v[164:165], v[80:81], v[224:225], v[164:165]
	v_pk_fma_f32 v[166:167], v[74:75], v[226:227], v[166:167]
	v_pk_fma_f32 v[168:169], v[76:77], v[228:229], v[168:169]
	v_pk_fma_f32 v[170:171], v[70:71], v[230:231], v[170:171]
	v_pk_fma_f32 v[172:173], v[72:73], v[232:233], v[172:173]
	v_pk_fma_f32 v[174:175], v[66:67], v[234:235], v[174:175]
	v_pk_fma_f32 v[176:177], v[68:69], v[236:237], v[176:177]
	flat_store_dwordx4 v[102:103], v[238:241]
	flat_store_dwordx4 v[102:103], v[242:245] offset:64
	flat_store_dwordx4 v[102:103], v[246:249] offset:128
	flat_store_dwordx4 v[102:103], v[158:161] offset:192
	flat_store_dwordx4 v[102:103], v[162:165] offset:256
	flat_store_dwordx4 v[102:103], v[166:169] offset:320
	flat_store_dwordx4 v[102:103], v[170:173] offset:384
	flat_store_dwordx4 v[102:103], v[174:177] offset:448
	s_nop 1
	v_or_b32_e32 v70, 32, v130
	v_cmp_gt_i32_e64 s[6:7], s4, v70
	s_movk_i32 s4, 0x3fff
	v_cmp_lt_i32_e64 s[4:5], s4, v70
	s_cbranch_vccnz .LBB0_83
	v_ashrrev_i32_e32 v71, 31, v70
	s_mov_b64 s[14:15], 0

;     __device__ __forceinline__ float* mod() const { return (float*)(ws + OFF_mod); }
; DEV void resid_big(const Params& p, int l, int mt, int nt, const bf16_t* A, int K, const bf16_t* W, int gate_off, bool res_from_input, char* smem) {
;     ...
;     for (int mi = 0; mi < 4; ++mi) {
;         const int row = rbase + mi * 16;
;         const float* gt = p.mod() + (size_t)(l * 9 + mod_index(row)) * 6144 + gate_off + c0;
;         const float* res = res_from_input ? xrow(p, l, row) : p.out + (size_t)row * 1024;
;         float* dst = p.out + (size_t)row * 1024;
; #pragma unroll
;         for (int ni = 0; ni < 8; ++ni) {
;             const f32x4 g4 = *(const f32x4*)(gt + ni * 16), r4 = *(const f32x4*)(res + c0 + ni * 16);
;             *(f32x4*)(dst + c0 + ni * 16) = r4 + g4 * acc[mi][ni];
;         }
;     }
.LBB0_89:
	v_lshrrev_b32_e32 v66, 4, v66
	v_or_b32_e32 v66, 1, v66
	v_cndmask_b32_e64 v66, v66, 0, s[6:7]
	v_add_u32_e32 v74, s20, v66
	v_mov_b64_e32 v[66:67], s[12:13]
	v_mad_i64_i32 v[66:67], s[4:5], v74, s33, v[66:67]
	v_lshl_add_u64 v[76:77], v[66:67], 0, v[32:33]
	v_lshlrev_b64 v[66:67], 12, v[68:69]
	v_lshl_add_u64 v[66:67], v[72:73], 0, v[66:67]
	v_add_co_u32_e32 v72, vcc, s34, v76
	v_lshl_add_u64 v[78:79], v[66:67], 0, v[32:33]
	s_nop 0
	v_addc_co_u32_e32 v73, vcc, 0, v77, vcc
	v_lshlrev_b64 v[70:71], 12, v[70:71]
	v_lshl_add_u64 v[70:71], s[92:93], 0, v[70:71]
	v_lshl_add_u64 v[70:71], v[70:71], 0, v[32:33]
	s_mov_b64 s[4:5], 0x2000
	v_lshl_add_u64 v[76:77], v[76:77], 0, s[4:5]
	s_and_b64 vcc, exec, s[0:1]
	s_movk_i32 s0, 0x4000
	s_movk_i32 s4, 0x3fff
	s_mov_b64 s[6:7], -1
	flat_load_dwordx4 v[206:209], v[72:73]
	flat_load_dwordx4 v[210:213], v[76:77] offset:64
	flat_load_dwordx4 v[214:217], v[76:77] offset:128
	flat_load_dwordx4 v[218:221], v[76:77] offset:192
	flat_load_dwordx4 v[222:225], v[76:77] offset:256
	flat_load_dwordx4 v[226:229], v[76:77] offset:320
	flat_load_dwordx4 v[230:233], v[76:77] offset:384
	flat_load_dwordx4 v[234:237], v[76:77] offset:448
	flat_load_dwordx4 v[238:241], v[78:79]
	flat_load_dwordx4 v[242:245], v[78:79] offset:64
	flat_load_dwordx4 v[246:249], v[78:79] offset:128
	flat_load_dwordx4 v[158:161], v[78:79] offset:192
	flat_load_dwordx4 v[162:165], v[78:79] offset:256
	flat_load_dwordx4 v[166:169], v[78:79] offset:320
	flat_load_dwordx4 v[170:173], v[78:79] offset:384
	flat_load_dwordx4 v[174:177], v[78:79] offset:448
	s_waitcnt vmcnt(0) lgkmcnt(0)
	v_pk_fma_f32 v[238:239], v[62:63], v[206:207], v[238:239]
	v_pk_fma_f32 v[240:241], v[64:65], v[208:209], v[240:241]
	v_pk_fma_f32 v[242:243], v[58:59], v[210:211], v[242:243]
	v_pk_fma_f32 v[244:245], v[60:61], v[212:213], v[244:245]
	v_pk_fma_f32 v[246:247], v[54:55], v[214:215], v[246:247]
	v_pk_fma_f32 v[248:249], v[56:57], v[216:217], v[248:249]
	v_pk_fma_f32 v[158:159], v[50:51], v[218:219], v[158:159]
	v_pk_fma_f32 v[160:161], v[52:53], v[220:221], v[160:161]
	v_pk_fma_f32 v[162:163], v[46:47], v[222:223], v[162:163]
	v_pk_fma_f32 v[164:165], v[48:49], v[224:225], v[164:165]
	v_pk_fma_f32 v[166:167], v[42:43], v[226:227], v[166:167]
	v_pk_fma_f32 v[168:169], v[44:45], v[228:229], v[168:169]
	v_pk_fma_f32 v[170:171], v[38:39], v[230:231], v[170:171]
	v_pk_fma_f32 v[172:173], v[40:41], v[232:233], v[172:173]
	v_pk_fma_f32 v[174:175], v[34:35], v[234:235], v[174:175]
	v_pk_fma_f32 v[176:177], v[36:37], v[236:237], v[176:177]
	flat_store_dwordx4 v[70:71], v[238:241]
	flat_store_dwordx4 v[70:71], v[242:245] offset:64
	flat_store_dwordx4 v[70:71], v[246:249] offset:128
	flat_store_dwordx4 v[70:71], v[158:161] offset:192
	flat_store_dwordx4 v[70:71], v[162:165] offset:256
	flat_store_dwordx4 v[70:71], v[166:169] offset:320
	flat_store_dwordx4 v[70:71], v[170:173] offset:384
	flat_store_dwordx4 v[70:71], v[174:177] offset:448
	s_nop 1
	v_or_b32_e32 v38, 48, v130
	v_cmp_gt_i32_e64 s[0:1], s0, v38
	v_cmp_lt_i32_e64 s[4:5], s4, v38
	s_cbranch_vccnz .LBB0_91
	v_ashrrev_i32_e32 v39, 31, v38
	s_mov_b64 s[6:7], 0
